# v014 plus NA loop L2 prefetch of the tile after next (4-byte LDS-DMA into unused LDS scratch, end-of-tile waits vmcnt(1))
# baseline (speedup 1.0000x reference)
; template <bool QL>
; __device__ __forceinline__ void qkt(f32x16& p0, f32x16& p1, const bf16* Ks, const bf16x8* qr, const char* ql, int r32, int hi) {
;   p0 = f32x16{}; p1 = f32x16{};
;   for (int d0 = 0; d0 < 8; ++d0) { int cb = (d0 * 16 + hi * 8) * 2;
;     bf16x8 b0 = *reinterpret_cast<const bf16x8*>((const char*)Ks + KSWZ(r32, cb));
;     bf16x8 b1 = *reinterpret_cast<const bf16x8*>((const char*)Ks + KSWZ(32 + r32, cb));
;     bf16x8 q; if constexpr (QL) q = *reinterpret_cast<const bf16x8*>(ql + d0 * 1024); else q = qr[d0];
;     p0 = __builtin_amdgcn_mfma_f32_32x32x16_bf16(b0, q, p0, 0, 0, 0);
;     p1 = __builtin_amdgcn_mfma_f32_32x32x16_bf16(b1, q, p1, 0, 0, 0); }
; }
; __device__ __forceinline__ void na_mask(f32x16& p0, f32x16& p1, int kr, int r0, int qrow, int qc, int c0, int hi, const float* bl) {
;   const bool tv = (kr >= r0) && (kr < r0 + 8);
;   if (!tv) {
; #pragma unroll
;     for (int r = 0; r < 16; ++r) { p0[r] = -1e30f; p1[r] = -1e30f; }
.LBB0_182:
	s_lshl_b32 s39, s17, 14
	s_add_i32 s1, s39, 0
	v_lshl_add_u64 v[160:161], s[28:29], 0, v[132:133]
	s_mov_b64 s[18:19], 0x1f520800
	s_add_i32 s14, s1, s33
	v_lshl_add_u64 v[64:65], v[160:161], 0, s[18:19]
	s_add_i32 m0, s14, 0xc000
	v_lshl_add_u64 v[162:163], s[28:29], 0, v[134:135]
	s_mov_b64 vcc, 0x1f521000
	global_load_lds_dwordx4 v[64:65], off
	v_lshl_add_u64 v[64:65], v[162:163], 0, vcc
	s_mov_b32 m0, s14
	v_lshl_add_u64 v[164:165], s[28:29], 0, v[136:137]
	global_load_lds_dwordx4 v[64:65], off
	v_lshl_add_u64 v[64:65], v[164:165], 0, s[18:19]
	s_add_i32 m0, s14, 0xc400
	v_lshl_add_u64 v[166:167], s[28:29], 0, v[142:143]
	global_load_lds_dwordx4 v[64:65], off
	v_lshl_add_u64 v[64:65], v[166:167], 0, vcc
	s_add_i32 m0, s14, 0x400
	s_nop 0
	global_load_lds_dwordx4 v[64:65], off
	s_lshr_b32 s98, s33, 11
	s_and_b32 s99, s98, 3
	s_mul_i32 s99, s99, 0x24000
	s_lshr_b32 s98, s98, 2
	s_lshl_b32 s98, s98, 11
	s_add_u32 s99, s99, s98
	s_add_u32 s100, s28, 0x1f5b0800
	s_addc_u32 s101, s29, 0
	s_add_u32 s100, s100, s99
	s_addc_u32 s101, s101, 0
	v_lshrrev_b32_e32 v64, 2, v202
	v_mul_u32_u24_e32 v64, 0x2400, v64
	v_bfe_u32 v65, v202, 1, 1
	v_lshl_or_b32 v64, v65, 7, v64
	v_mov_b32_e32 v65, 0
	v_lshl_add_u64 v[64:65], s[100:101], 0, v[64:65]
	s_lshr_b32 s98, s33, 3
	s_add_i32 m0, s98, 0x21000
	s_nop 0
	global_load_lds_dword v[64:65], off
	s_lshl_b32 s30, s0, 14
	s_add_i32 s0, s30, 0
	v_add_u32_e32 v68, s0, v173
	ds_read_b128 v[64:67], v68 offset:49152
	ds_read_b128 v[68:71], v68 offset:57344
	v_add_u32_e32 v195, s0, v174
	ds_read_b128 v[196:199], v195 offset:49152
	ds_read_b128 v[222:225], v195 offset:57344
	v_add_u32_e32 v195, s0, v175
	s_waitcnt lgkmcnt(0)
	v_mfma_f32_32x32x16_bf16 v[80:95], v[64:67], v[100:103], 0
	s_add_i32 s22, s37, s27
	v_mov_b32_e32 v241, 0xf149f2ca
	v_mov_b32_e32 v242, 0xf149f2ca
	v_mov_b32_e32 v243, 0xf149f2ca
	v_mov_b32_e32 v246, 0xf149f2ca
	v_mov_b32_e32 v247, 0xf149f2ca
	v_mov_b32_e32 v248, 0xf149f2ca
	v_mfma_f32_32x32x16_bf16 v[64:79], v[68:71], v[100:103], 0
	v_mov_b32_e32 v249, 0xf149f2ca
	v_mov_b32_e32 v250, 0xf149f2ca
	v_mov_b32_e32 v251, 0xf149f2ca
	v_mov_b32_e32 v237, 0xf149f2ca
	v_mov_b32_e32 v235, 0xf149f2ca
	v_mov_b32_e32 v203, 0xf149f2ca
	v_mov_b32_e32 v244, 0xf149f2ca
	v_mfma_f32_32x32x16_bf16 v[80:95], v[196:199], v[126:129], v[80:95]
	v_mov_b32_e32 v245, 0xf149f2ca
	v_mov_b32_e32 v238, 0xf149f2ca
	v_mov_b32_e32 v240, 0xf149f2ca
	v_mov_b32_e32 v234, 0xf149f2ca
	v_mov_b32_e32 v236, 0xf149f2ca
	v_mov_b32_e32 v230, 0xf149f2ca
	v_mov_b32_e32 v232, 0xf149f2ca
	v_mfma_f32_32x32x16_bf16 v[64:79], v[222:225], v[126:129], v[64:79]
	ds_read_b128 v[196:199], v195 offset:49152
	ds_read_b128 v[222:225], v195 offset:57344
	v_add_u32_e32 v195, s0, v176
	v_mov_b32_e32 v228, 0xf149f2ca
	v_mov_b32_e32 v229, 0xf149f2ca
	v_mov_b32_e32 v226, 0xf149f2ca
	v_mov_b32_e32 v221, 0xf149f2ca
	s_waitcnt lgkmcnt(0)
	v_mfma_f32_32x32x16_bf16 v[80:95], v[196:199], v[122:125], v[80:95]
	v_mfma_f32_32x32x16_bf16 v[64:79], v[222:225], v[122:125], v[64:79]
	ds_read_b128 v[196:199], v195 offset:49152
	ds_read_b128 v[222:225], v195 offset:57344
	v_add_u32_e32 v195, s0, v177
	s_waitcnt lgkmcnt(0)
	v_mfma_f32_32x32x16_bf16 v[80:95], v[196:199], v[118:121], v[80:95]
	v_mfma_f32_32x32x16_bf16 v[64:79], v[222:225], v[118:121], v[64:79]
	ds_read_b128 v[196:199], v195 offset:49152
	ds_read_b128 v[222:225], v195 offset:57344
	v_add_u32_e32 v195, s0, v178
	s_waitcnt lgkmcnt(0)
	v_mfma_f32_32x32x16_bf16 v[80:95], v[196:199], v[114:117], v[80:95]
	v_mfma_f32_32x32x16_bf16 v[64:79], v[222:225], v[114:117], v[64:79]
	ds_read_b128 v[196:199], v195 offset:49152
	ds_read_b128 v[222:225], v195 offset:57344
	v_add_u32_e32 v195, s0, v179
	s_waitcnt lgkmcnt(0)
	v_mfma_f32_32x32x16_bf16 v[80:95], v[196:199], v[108:111], v[80:95]
	v_mfma_f32_32x32x16_bf16 v[64:79], v[222:225], v[108:111], v[64:79]
	ds_read_b128 v[196:199], v195 offset:49152
	ds_read_b128 v[222:225], v195 offset:57344
	v_add_u32_e32 v195, s0, v180
	s_add_i32 s0, s22, -6
	v_cmp_ge_u32_e32 vcc, s0, v190
	v_cmp_lt_u32_e64 s[18:19], s0, v191
	s_and_b64 s[14:15], vcc, s[18:19]
	s_waitcnt lgkmcnt(0)
	v_mfma_f32_32x32x16_bf16 v[80:95], v[196:199], v[104:107], v[80:95]
	v_mfma_f32_32x32x16_bf16 v[64:79], v[222:225], v[104:107], v[64:79]
	ds_read_b128 v[196:199], v195 offset:49152
	ds_read_b128 v[222:225], v195 offset:57344
	s_waitcnt lgkmcnt(0)
	v_mfma_f32_32x32x16_bf16 v[80:95], v[196:199], v[96:99], v[80:95]
	v_mov_b32_e32 v196, 0xf149f2ca
	v_mov_b32_e32 v197, 0xf149f2ca
	v_mov_b32_e32 v198, 0xf149f2ca
	v_mov_b32_e32 v199, 0xf149f2ca
	v_mfma_f32_32x32x16_bf16 v[64:79], v[222:225], v[96:99], v[64:79]
	v_mov_b32_e32 v225, 0xf149f2ca
	v_mov_b32_e32 v223, 0xf149f2ca
	v_mov_b32_e32 v224, 0xf149f2ca
	v_mov_b32_e32 v222, 0xf149f2ca
	s_and_saveexec_b64 s[18:19], s[14:15]
	s_cbranch_execz .LBB0_216
; __device__ __forceinline__ void na_mask(f32x16& p0, f32x16& p1, int kr, int r0, int qrow, int qc, int c0, int hi, const float* bl) {
;   const bool tv = (kr >= r0) && (kr < r0 + 8);
;   if (!tv) {
; #pragma unroll
;     for (int r = 0; r < 16; ++r) { p0[r] = -1e30f; p1[r] = -1e30f; }
;   } else {
;     const float* brow = bl + (kr - qrow + 7) * 31 + 15 - qc + 4 * hi;
;     const int d = 4 * hi - c0;
; #pragma unroll
;     for (int r = 0; r < 16; ++r) {
;       const int kc = (r & 3) + 8 * (r >> 2);
;       const float b0 = brow[kc], b1 = brow[kc + 32];
;       p0[r] = (unsigned)(d + kc) < 16u ? p0[r] + b0 : -1e30f; p1[r] = (unsigned)(d + kc + 32) < 16u ? p1[r] + b1 : -1e30f;
;     }
;   }
	ds_read_b32 v195, v193 offset:128
	v_mov_b32_e32 v221, 0xf149f2ca
	v_mov_b32_e32 v222, 0xf149f2ca
	v_mov_b32_e32 v223, 0xf149f2ca
	v_mov_b32_e32 v224, 0xf149f2ca
	v_mov_b32_e32 v225, 0xf149f2ca
	v_mov_b32_e32 v226, 0xf149f2ca
	v_mov_b32_e32 v228, 0xf149f2ca
	v_mov_b32_e32 v229, 0xf149f2ca
	v_mov_b32_e32 v230, 0xf149f2ca
	v_mov_b32_e32 v232, 0xf149f2ca
	v_mov_b32_e32 v234, 0xf149f2ca
	v_mov_b32_e32 v236, 0xf149f2ca
	v_mov_b32_e32 v238, 0xf149f2ca
	v_mov_b32_e32 v240, 0xf149f2ca
	v_mov_b32_e32 v244, 0xf149f2ca
	v_mov_b32_e32 v245, 0xf149f2ca
	ds_read_b32 v222, v193
	ds_read_b32 v221, v193 offset:4
	ds_read_b32 v224, v193 offset:8
	ds_read_b32 v223, v193 offset:12
	ds_read_b32 v226, v193 offset:32
	ds_read_b32 v225, v193 offset:36
	ds_read_b32 v229, v193 offset:40
	ds_read_b32 v228, v193 offset:44
	ds_read_b32 v232, v193 offset:64
	ds_read_b32 v230, v193 offset:68
	ds_read_b32 v236, v193 offset:72
	ds_read_b32 v234, v193 offset:76
	ds_read_b32 v240, v193 offset:96
	ds_read_b32 v238, v193 offset:100
	ds_read_b32 v245, v193 offset:104
	ds_read_b32 v244, v193 offset:108
	s_waitcnt lgkmcnt(0)
	v_add_f32_e32 v222, v80, v222
	v_add_f32_e32 v221, v81, v221
	v_add_f32_e32 v224, v82, v224
	v_add_f32_e32 v223, v83, v223
	v_add_f32_e32 v226, v84, v226
	v_add_f32_e32 v225, v85, v225
	v_add_f32_e32 v229, v86, v229
	v_add_f32_e32 v228, v87, v228
	v_add_f32_e32 v232, v88, v232
	v_add_f32_e32 v230, v89, v230
	v_add_f32_e32 v236, v90, v236
	v_add_f32_e32 v234, v91, v234
	v_add_f32_e32 v240, v92, v240
	v_add_f32_e32 v238, v93, v238
	v_add_f32_e32 v245, v94, v245
	v_add_f32_e32 v244, v95, v244
	ds_read_b32 v80, v193 offset:132
	ds_read_b32 v81, v193 offset:136
	ds_read_b32 v82, v193 offset:140
	ds_read_b32 v83, v193 offset:160
	ds_read_b32 v84, v193 offset:164
	ds_read_b32 v85, v193 offset:168
	ds_read_b32 v86, v193 offset:172
	ds_read_b32 v87, v193 offset:192
	ds_read_b32 v88, v193 offset:196
	ds_read_b32 v89, v193 offset:200
	ds_read_b32 v90, v193 offset:204
	ds_read_b32 v91, v193 offset:224
	ds_read_b32 v92, v193 offset:228
	ds_read_b32 v196, v193 offset:232
	ds_read_b32 v93, v193 offset:236
	v_cndmask_b32_e64 v222, v239, v222, s[42:43]
	v_cndmask_b32_e64 v221, v239, v221, s[46:47]
	v_cndmask_b32_e64 v224, v239, v224, s[50:51]
	v_cndmask_b32_e64 v223, v239, v223, s[54:55]
	v_cndmask_b32_e64 v226, v239, v226, s[58:59]
	v_cndmask_b32_e64 v225, v239, v225, s[62:63]
	v_cndmask_b32_e64 v229, v239, v229, s[66:67]
	v_cndmask_b32_e64 v228, v239, v228, s[70:71]
	v_cndmask_b32_e64 v232, v239, v232, s[74:75]
	v_cndmask_b32_e64 v230, v239, v230, s[78:79]
	v_cndmask_b32_e64 v236, v239, v236, s[82:83]
	v_cndmask_b32_e64 v234, v239, v234, s[86:87]
	v_cndmask_b32_e64 v240, v239, v240, s[90:91]
	v_cndmask_b32_e64 v238, v239, v238, s[94:95]
	v_cndmask_b32_e64 v245, v239, v245, s[4:5]
	v_cndmask_b32_e64 v244, v239, v244, s[8:9]
	s_waitcnt lgkmcnt(0)
	v_add_f32_e32 v64, v64, v195
	v_add_f32_e32 v78, v78, v196
	v_add_f32_e32 v77, v77, v92
	v_add_f32_e32 v76, v76, v91
	v_add_f32_e32 v75, v75, v90
	v_add_f32_e32 v74, v74, v89
	v_add_f32_e32 v73, v73, v88
	v_add_f32_e32 v72, v72, v87
	v_add_f32_e32 v71, v71, v86
	v_add_f32_e32 v70, v70, v85
	v_add_f32_e32 v69, v69, v84
	v_add_f32_e32 v68, v68, v83
	v_add_f32_e32 v67, v67, v82
	v_add_f32_e32 v66, v66, v81
	v_add_f32_e32 v65, v65, v80
	v_cndmask_b32_e64 v198, v239, v64, s[44:45]
	v_add_f32_e32 v64, v79, v93
	v_cndmask_b32_e64 v241, v239, v78, s[6:7]
	v_cndmask_b32_e64 v242, v239, v77, s[96:97]
	v_cndmask_b32_e64 v243, v239, v76, s[92:93]
	v_cndmask_b32_e64 v246, v239, v75, s[88:89]
	v_cndmask_b32_e64 v247, v239, v74, s[84:85]
	v_cndmask_b32_e64 v248, v239, v73, s[80:81]
	v_cndmask_b32_e64 v249, v239, v72, s[76:77]
	v_cndmask_b32_e64 v250, v239, v71, s[72:73]
	v_cndmask_b32_e64 v251, v239, v70, s[68:69]
	v_cndmask_b32_e64 v237, v239, v69, s[64:65]
	v_cndmask_b32_e64 v235, v239, v68, s[60:61]
	v_cndmask_b32_e64 v203, v239, v67, s[56:57]
	v_cndmask_b32_e64 v196, v239, v66, s[52:53]
	v_cndmask_b32_e64 v197, v239, v65, s[48:49]
	v_cndmask_b32_e64 v199, v239, v64, s[10:11]

; #define VM0() asm volatile("s_waitcnt vmcnt(0)" ::: "memory")
; template <bool NA, int ROWB>
; __device__ __forceinline__ void attn_dma(const bf16* __restrict__ Qb, const bf16* __restrict__ Kh, const bf16* __restrict__ Vh, bf16* __restrict__ Ob, int NT, char* lds, const int tid, float* __restrict__ ssb, int qrow0, int kr_lo, const float* bl) {
;     ...
;     VM0(); __syncthreads();
;     bp = bc; bc = bn; bn = NEXTB(bn);
;     if (t + 2 < NT) DMA_TILE(t + 2, bn);
.LBB0_220:
	s_waitcnt vmcnt(1)
	s_add_i32 s0, s17, 1
	s_cmp_lg_u32 s17, 2
	s_cselect_b32 s0, s0, 0
	s_cmp_ge_u32 s27, s16
	s_waitcnt vmcnt(1)
	s_barrier
	s_cbranch_scc1 .LBB0_222
	s_lshl_b32 s14, s0, 14
	s_mov_b64 vcc, 0x1f5b0800
	s_add_i32 s14, s38, s14
	v_lshl_add_u64 v[64:65], v[160:161], 0, vcc
	s_add_i32 m0, s14, 0xc000
	s_mov_b64 s[40:41], 0x1f5b1000
	global_load_lds_dwordx4 v[64:65], off
	v_lshl_add_u64 v[64:65], v[162:163], 0, s[40:41]
	s_mov_b32 m0, s14
	s_nop 0
	global_load_lds_dwordx4 v[64:65], off
	v_lshl_add_u64 v[64:65], v[164:165], 0, vcc
	s_add_i32 m0, s14, 0xc400
	s_nop 0
	global_load_lds_dwordx4 v[64:65], off
	v_lshl_add_u64 v[64:65], v[166:167], 0, s[40:41]
	s_add_i32 m0, s14, 0x400
	s_nop 0
	global_load_lds_dwordx4 v[64:65], off
	s_lshr_b32 s98, s38, 11
	s_and_b32 s99, s98, 3
	s_mul_i32 s99, s99, 0x24000
	s_lshr_b32 s98, s98, 2
	s_lshl_b32 s98, s98, 11
	s_add_u32 s99, s99, s98
	s_add_u32 s100, s28, 0x1f640800
	s_addc_u32 s101, s29, 0
	s_add_u32 s100, s100, s99
	s_addc_u32 s101, s101, 0
	v_lshrrev_b32_e32 v64, 2, v202
	v_mul_u32_u24_e32 v64, 0x2400, v64
	v_bfe_u32 v65, v202, 1, 1
	v_lshl_or_b32 v64, v65, 7, v64
	v_mov_b32_e32 v65, 0
	v_lshl_add_u64 v[64:65], s[100:101], 0, v[64:65]
	s_lshr_b32 s98, s38, 3
	s_add_i32 m0, s98, 0x21000
	s_nop 0
	global_load_lds_dword v[64:65], off

; #define PSM(P0, P1, MN, AL) do { if constexpr (NA) partialSM(P0, P1, m_reg, MN, AL); else { AL = 1.f; _Pragma("unroll") for (int r = 0; r < 16; ++r) P0[r] = __builtin_amdgcn_exp2f(P0[r]); } } while (0)
; #define RESCN(a) do { if constexpr (NA) RESC(a); } while (0)
; #define VM0() asm volatile("s_waitcnt vmcnt(0)" ::: "memory")
; #define PSM(P0, P1, MN, AL) do { if constexpr (NA) partialSM(P0, P1, m_reg, MN, AL); else { AL = 1.f; _Pragma("unroll") for (int r = 0; r < 16; ++r) P0[r] = __builtin_amdgcn_exp2f(P0[r]); } } while (0)
; #define RESCN(a) do { if constexpr (NA) RESC(a); } while (0)
; __device__ __forceinline__ void partialSM(f32x16& p0, f32x16& p1, float& m_reg, float& mn, float& alpha) {
;   constexpr float C = SCALE * 1.4426950408889634f;
;   float pmax = p0[0]; for (int r = 1; r < 16; ++r) pmax = fmaxf(pmax, p0[r]); for (int r = 0; r < 16; ++r) pmax = fmaxf(pmax, p1[r]);
;   { auto rr = __builtin_amdgcn_permlane32_swap(__float_as_uint(pmax), __float_as_uint(pmax), false, false);
;     pmax = fmaxf(__uint_as_float(rr[0]), __uint_as_float(rr[1])); }
;   if (__builtin_expect(__all(pmax - m_reg <= THR / SCALE), 1)) { mn = m_reg; alpha = 1.f; }
;   else { mn = fmaxf(m_reg, pmax); alpha = __builtin_amdgcn_exp2f((m_reg - mn) * C); m_reg = mn; }
;   float mnC = -mn * C;
;   for (int r = 0; r < 16; ++r) p0[r] = fmaf(p0[r], C, mnC); for (int r = 0; r < 16; ++r) p1[r] = fmaf(p1[r], C, mnC);
;   for (int r = 0; r < 16; ++r) p0[r] = __builtin_amdgcn_exp2f(p0[r]);
; template <bool NA, int ROWB>
; __device__ __forceinline__ void attn_dma(const bf16* __restrict__ Qb, const bf16* __restrict__ Kh, const bf16* __restrict__ Vh, bf16* __restrict__ Ob, int NT, char* lds, const int tid, float* __restrict__ ssb, int qrow0, int kr_lo, const float* bl) {
;     ...
;     pv_d0(o, vb0 + bp * (int)SHM_V, pa0, pa1, pa2, pa3); PSM(pA0, pA1, mnA, alA); RESCN(alA);
;     VM0(); __syncthreads();
;     bp = bc; bc = bn; bn = NEXTB(bn);
;   }
.LBB0_262:
	v_cndmask_b32_e64 v192, v67, v64, s[18:19]
	v_mul_f32_e32 v64, 0xbe0293ee, v192
	s_add_i32 s1, s0, 1
	v_fmamk_f32 v67, v162, 0x3e0293ee, v64
	v_fmamk_f32 v68, v161, 0x3e0293ee, v64
	v_fmamk_f32 v69, v164, 0x3e0293ee, v64
	v_fmamk_f32 v70, v163, 0x3e0293ee, v64
	v_fmamk_f32 v71, v166, 0x3e0293ee, v64
	v_fmamk_f32 v72, v165, 0x3e0293ee, v64
	v_fmamk_f32 v73, v205, 0x3e0293ee, v64
	v_fmamk_f32 v74, v167, 0x3e0293ee, v64
	v_fmamk_f32 v75, v207, 0x3e0293ee, v64
	v_fmamk_f32 v76, v206, 0x3e0293ee, v64
	v_fmamk_f32 v77, v209, 0x3e0293ee, v64
	v_fmamk_f32 v78, v208, 0x3e0293ee, v64
	v_fmamk_f32 v79, v211, 0x3e0293ee, v64
	v_fmamk_f32 v80, v210, 0x3e0293ee, v64
	v_fmamk_f32 v81, v213, 0x3e0293ee, v64
	v_fmamk_f32 v82, v212, 0x3e0293ee, v64
	s_cmp_lg_u32 s0, 2
	v_exp_f32_e32 v213, v67
	v_exp_f32_e32 v217, v68
	v_exp_f32_e32 v214, v69
	v_exp_f32_e32 v218, v70
	v_exp_f32_e32 v215, v71
	v_exp_f32_e32 v219, v72
	v_exp_f32_e32 v216, v73
	v_exp_f32_e32 v220, v74
	v_exp_f32_e32 v205, v75
	v_exp_f32_e32 v209, v76
	v_exp_f32_e32 v206, v77
	v_exp_f32_e32 v210, v78
	v_exp_f32_e32 v207, v79
	v_exp_f32_e32 v211, v80
	v_exp_f32_e32 v208, v81
	v_exp_f32_e32 v212, v82
	s_cselect_b32 s1, s1, 0
	s_add_i32 s14, s27, 2
	v_add_f32_e32 v67, v195, v204
	s_waitcnt vmcnt(1)
	s_add_u32 s28, s28, 0x120000
	v_fmac_f32_e32 v67, v188, v194
	v_add_f32_e32 v188, v65, v66
	s_addc_u32 s29, s29, 0
	s_add_i32 s15, s27, 1
	v_fmac_f32_e32 v188, v67, v227
	v_pk_fma_f32 v[144:145], v[144:145], s[26:27], v[64:65] op_sel_hi:[1,0,0]
	v_pk_fma_f32 v[146:147], v[146:147], s[26:27], v[64:65] op_sel_hi:[1,0,0]
	v_pk_fma_f32 v[148:149], v[148:149], s[26:27], v[64:65] op_sel_hi:[1,0,0]
	v_pk_fma_f32 v[150:151], v[150:151], s[26:27], v[64:65] op_sel_hi:[1,0,0]
	v_pk_fma_f32 v[152:153], v[152:153], s[26:27], v[64:65] op_sel_hi:[1,0,0]
	v_pk_fma_f32 v[154:155], v[154:155], s[26:27], v[64:65] op_sel_hi:[1,0,0]
	v_pk_fma_f32 v[156:157], v[156:157], s[26:27], v[64:65] op_sel_hi:[1,0,0]
	v_pk_fma_f32 v[158:159], v[158:159], s[26:27], v[64:65] op_sel_hi:[1,0,0]
	s_cmp_ge_u32 s15, s16
	v_add_u32_e32 v193, 0xf8, v193
	s_waitcnt vmcnt(1)
	s_barrier
	s_cbranch_scc1 .LBB0_264
	s_mov_b32 s27, s14
	s_mov_b32 s23, s17
	s_mov_b32 s17, s1
	v_mov_b32_e32 v194, v160
	s_branch .LBB0_182
